# P3 loop: barrier moved behind PV MFMA 11; PV MFMAs 12-15 of the previous tile run after the barrier behind the next tile's K reads and LDS-DMA
# speedup vs baseline: 1.0012x; 1.0012x over previous
.LBB0_323:
	s_and_b32 s1, s79, 0x18000
	s_xor_b32 s0, s1, 0x10000
	v_add_u32_e32 v158, s0, v222
	v_add_u32_e32 v159, s0, v223
	v_add_u32_e32 v160, s0, v241
	v_add_u32_e32 v161, s0, v242
	ds_read_b128 v[80:83], v158 offset:16384
	ds_read_b128 v[84:87], v159 offset:16384
	ds_read_b128 v[88:91], v160 offset:16384
	ds_read_b128 v[186:189], v161 offset:16384
	ds_read_b128 v[246:249], v158 offset:20480
	ds_read_b128 v[250:253], v159 offset:20480
	s_cmp_ge_i32 s72, s98
	s_cbranch_scc1 .Lk_nodmae
	s_add_i32 m0, s1, s94
	s_add_i32 s4, s90, s1
	global_load_lds_dwordx4 v[220:221], off
	s_mov_b32 m0, s4
	s_add_i32 s4, s1, s66
	global_load_lds_dwordx4 v[218:219], off
	s_mov_b32 m0, s4
	global_load_lds_dwordx4 v[224:225], off
	global_load_lds_dwordx4 v[224:225], off offset:1024

.Lk_top:
	ds_read_b128 v[80:83], v158 offset:16384
	ds_read_b128 v[84:87], v159 offset:16384
	ds_read_b128 v[88:91], v160 offset:16384
	ds_read_b128 v[186:189], v161 offset:16384
	ds_read_b128 v[246:249], v158 offset:20480
	ds_read_b128 v[250:253], v159 offset:20480
	s_cmp_ge_i32 s72, s98
	s_cbranch_scc1 .Lk_nodmal
	s_add_i32 m0, s1, s94
	s_add_i32 s4, s90, s1
	global_load_lds_dwordx4 v[220:221], off
	s_mov_b32 m0, s4
	s_add_i32 s4, s1, s66
	global_load_lds_dwordx4 v[218:219], off
	s_mov_b32 m0, s4
	global_load_lds_dwordx4 v[224:225], off
	global_load_lds_dwordx4 v[224:225], off offset:1024
.Lk_nodmal:
	v_mfma_f32_32x32x16_bf16 v[48:63], v[182:185], v[166:169], v[48:63]
	v_add_f32_e32 v202, v255, v92
	v_exp_f32_e32 v202, v202
	v_cvt_pk_bf16_f32 v171, v192, v193
	v_add_f32_e32 v156, v202, v108
	v_add_f32_e32 v157, v156, v157
	v_mfma_f32_32x32x16_bf16 v[32:47], v[178:181], v[166:169], v[32:47]
	v_add_f32_e32 v203, v255, v93
	v_exp_f32_e32 v203, v203
	v_cvt_pk_bf16_f32 v172, v194, v195
	v_add_f32_e32 v156, v203, v109
	v_add_f32_e32 v157, v156, v157
	v_mfma_f32_32x32x16_bf16 v[16:31], v[148:151], v[166:169], v[16:31]
	v_add_f32_e32 v204, v255, v94
	v_exp_f32_e32 v204, v204
	v_cvt_pk_bf16_f32 v173, v196, v197
	v_add_f32_e32 v156, v204, v110
	v_add_f32_e32 v157, v156, v157
	v_mfma_f32_32x32x16_bf16 v[0:15], v[152:155], v[166:169], v[0:15]
	v_add_f32_e32 v205, v255, v95
	v_exp_f32_e32 v205, v205
	v_cvt_pk_bf16_f32 v166, v198, v199
	v_add_f32_e32 v156, v205, v111
	v_add_f32_e32 v157, v156, v157
	v_cvt_pk_bf16_f32 v167, v200, v201
	v_cvt_pk_bf16_f32 v168, v202, v203
	v_cvt_pk_bf16_f32 v169, v204, v205
	v_add_f32_e32 v229, v229, v157
.Lk_qk:
	s_waitcnt lgkmcnt(2)
	v_mfma_f32_32x32x16_bf16 v[96:111], v[80:83], v[144:147], v[64:79]
	ds_read_b128 v[190:193], v160 offset:20480
	ds_read_b128 v[194:197], v161 offset:20480
	v_mfma_f32_32x32x16_bf16 v[96:111], v[84:87], v[140:143], v[96:111]
	v_cvt_f32_i32_e32 v156, s100
	v_mfma_f32_32x32x16_bf16 v[96:111], v[88:91], v[136:139], v[96:111]
	v_fma_f32 v254, v208, v156, -v207
	v_mfma_f32_32x32x16_bf16 v[96:111], v[186:189], v[132:135], v[96:111]
	v_add_f32_e32 v255, v237, v254
	s_add_i32 s3, s79, 0xfffe8000
	s_and_b32 s3, s3, 0x18000
	v_add_u32_e32 v158, s3, v235
	v_add_u32_e32 v159, s3, v239
	v_add_u32_e32 v160, s3, v236
	v_add_u32_e32 v161, s3, v234
	ds_read_b64_tr_b16 v[182:183], v158 offset:32768
	ds_read_b64_tr_b16 v[184:185], v158 offset:34816
	ds_read_b64_tr_b16 v[178:179], v159 offset:32768
	ds_read_b64_tr_b16 v[180:181], v159 offset:34816
	ds_read_b64_tr_b16 v[148:149], v160 offset:32768
	ds_read_b64_tr_b16 v[150:151], v160 offset:34816
	ds_read_b64_tr_b16 v[152:153], v161 offset:32768
	ds_read_b64_tr_b16 v[154:155], v161 offset:34816
	s_waitcnt lgkmcnt(8)
	v_mfma_f32_32x32x16_bf16 v[80:95], v[246:249], v[144:147], v[64:79]
	v_add_f32_e32 v96, v254, v96
	v_exp_f32_e32 v96, v96
	v_add_f32_e32 v97, v254, v97
	v_exp_f32_e32 v97, v97
	v_add_f32_e32 v98, v254, v98
	v_exp_f32_e32 v98, v98
	v_add_f32_e32 v99, v254, v99
	v_exp_f32_e32 v99, v99
	v_mfma_f32_32x32x16_bf16 v[80:95], v[250:253], v[140:143], v[80:95]
	v_add_f32_e32 v100, v254, v100
	v_exp_f32_e32 v100, v100
	v_add_f32_e32 v101, v254, v101
	v_exp_f32_e32 v101, v101
	v_add_f32_e32 v102, v254, v102
	v_exp_f32_e32 v102, v102
	v_add_f32_e32 v103, v254, v103
	v_exp_f32_e32 v103, v103
	v_mfma_f32_32x32x16_bf16 v[80:95], v[190:193], v[136:139], v[80:95]
	v_add_f32_e32 v104, v254, v104
	v_exp_f32_e32 v104, v104
	v_add_f32_e32 v105, v254, v105
	v_exp_f32_e32 v105, v105
	v_add_f32_e32 v106, v254, v106
	v_exp_f32_e32 v106, v106
	v_add_f32_e32 v107, v254, v107
	v_exp_f32_e32 v107, v107
	v_mfma_f32_32x32x16_bf16 v[80:95], v[194:197], v[132:135], v[80:95]
	v_add_f32_e32 v108, v254, v108
	v_exp_f32_e32 v108, v108
	v_add_f32_e32 v109, v254, v109
	v_exp_f32_e32 v109, v109
	v_add_f32_e32 v110, v254, v110
	v_exp_f32_e32 v110, v110
	v_add_f32_e32 v111, v254, v111
	v_exp_f32_e32 v111, v111
	s_cmp_le_i32 s72, s101
	s_cbranch_scc0 .Lmask_blk
.LBB0_327:
	s_waitcnt lgkmcnt(4)
	v_mfma_f32_32x32x16_bf16 v[48:63], v[182:185], v[174:177], v[48:63]
	v_add_f32_e32 v190, v255, v80
	v_exp_f32_e32 v190, v190
	ds_read_b64_tr_b16 v[246:247], v158 offset:36864
	ds_read_b64_tr_b16 v[248:249], v158 offset:38912
	v_add_f32_e32 v157, v190, v96
	v_mfma_f32_32x32x16_bf16 v[32:47], v[178:181], v[174:177], v[32:47]
	v_add_f32_e32 v191, v255, v81
	v_exp_f32_e32 v191, v191
	ds_read_b64_tr_b16 v[250:251], v159 offset:36864
	ds_read_b64_tr_b16 v[252:253], v159 offset:38912
	v_add_f32_e32 v156, v191, v97
	v_add_f32_e32 v157, v156, v157
	s_waitcnt lgkmcnt(4)
	v_mfma_f32_32x32x16_bf16 v[16:31], v[148:151], v[174:177], v[16:31]
	v_add_f32_e32 v192, v255, v82
	v_exp_f32_e32 v192, v192
	ds_read_b64_tr_b16 v[182:183], v160 offset:36864
	ds_read_b64_tr_b16 v[184:185], v160 offset:38912
	v_add_f32_e32 v156, v192, v98
	v_add_f32_e32 v157, v156, v157
	v_mfma_f32_32x32x16_bf16 v[0:15], v[152:155], v[174:177], v[0:15]
	v_add_f32_e32 v193, v255, v83
	v_exp_f32_e32 v193, v193
	ds_read_b64_tr_b16 v[178:179], v161 offset:36864
	ds_read_b64_tr_b16 v[180:181], v161 offset:38912
	v_add_f32_e32 v156, v193, v99
	v_add_f32_e32 v157, v156, v157
	v_cvt_pk_bf16_f32 v174, v96, v97
	s_waitcnt lgkmcnt(4)
	v_mfma_f32_32x32x16_bf16 v[48:63], v[246:249], v[162:165], v[48:63]
	v_add_f32_e32 v194, v255, v84
	v_exp_f32_e32 v194, v194
	ds_read_b64_tr_b16 v[148:149], v158 offset:40960
	ds_read_b64_tr_b16 v[150:151], v158 offset:43008
	v_add_f32_e32 v156, v194, v100
	v_add_f32_e32 v157, v156, v157
	v_cvt_pk_bf16_f32 v175, v98, v99
	v_mfma_f32_32x32x16_bf16 v[32:47], v[250:253], v[162:165], v[32:47]
	v_add_f32_e32 v195, v255, v85
	v_exp_f32_e32 v195, v195
	ds_read_b64_tr_b16 v[152:153], v159 offset:40960
	ds_read_b64_tr_b16 v[154:155], v159 offset:43008
	v_add_f32_e32 v156, v195, v101
	v_add_f32_e32 v157, v156, v157
	v_cvt_pk_bf16_f32 v176, v100, v101
	s_waitcnt lgkmcnt(4)
	v_mfma_f32_32x32x16_bf16 v[16:31], v[182:185], v[162:165], v[16:31]
	v_add_f32_e32 v196, v255, v86
	v_exp_f32_e32 v196, v196
	ds_read_b64_tr_b16 v[246:247], v160 offset:40960
	ds_read_b64_tr_b16 v[248:249], v160 offset:43008
	v_add_f32_e32 v156, v196, v102
	v_add_f32_e32 v157, v156, v157
	v_cvt_pk_bf16_f32 v177, v102, v103
	v_mfma_f32_32x32x16_bf16 v[0:15], v[178:181], v[162:165], v[0:15]
	v_add_f32_e32 v197, v255, v87
	v_exp_f32_e32 v197, v197
	ds_read_b64_tr_b16 v[250:251], v161 offset:40960
	ds_read_b64_tr_b16 v[252:253], v161 offset:43008
	v_add_f32_e32 v156, v197, v103
	v_add_f32_e32 v157, v156, v157
	v_cvt_pk_bf16_f32 v162, v104, v105
	s_waitcnt lgkmcnt(4)
	v_mfma_f32_32x32x16_bf16 v[48:63], v[148:151], v[170:173], v[48:63]
	v_add_f32_e32 v198, v255, v88
	v_exp_f32_e32 v198, v198
	ds_read_b64_tr_b16 v[182:183], v158 offset:45056
	ds_read_b64_tr_b16 v[184:185], v158 offset:47104
	v_add_f32_e32 v156, v198, v104
	v_add_f32_e32 v157, v156, v157
	v_cvt_pk_bf16_f32 v163, v106, v107
	v_mfma_f32_32x32x16_bf16 v[32:47], v[152:155], v[170:173], v[32:47]
	v_add_f32_e32 v199, v255, v89
	v_exp_f32_e32 v199, v199
	ds_read_b64_tr_b16 v[178:179], v159 offset:45056
	ds_read_b64_tr_b16 v[180:181], v159 offset:47104
	v_add_f32_e32 v156, v199, v105
	v_add_f32_e32 v157, v156, v157
	v_cvt_pk_bf16_f32 v164, v108, v109
	s_waitcnt lgkmcnt(4)
	v_mfma_f32_32x32x16_bf16 v[16:31], v[246:249], v[170:173], v[16:31]
	v_add_f32_e32 v200, v255, v90
	v_exp_f32_e32 v200, v200
	ds_read_b64_tr_b16 v[148:149], v160 offset:45056
	ds_read_b64_tr_b16 v[150:151], v160 offset:47104
	v_add_f32_e32 v156, v200, v106
	v_add_f32_e32 v157, v156, v157
	v_cvt_pk_bf16_f32 v165, v110, v111
	v_mfma_f32_32x32x16_bf16 v[0:15], v[250:253], v[170:173], v[0:15]
	v_add_f32_e32 v201, v255, v91
	v_exp_f32_e32 v201, v201
	ds_read_b64_tr_b16 v[152:153], v161 offset:45056
	ds_read_b64_tr_b16 v[154:155], v161 offset:47104
	v_add_f32_e32 v156, v201, v107
	v_add_f32_e32 v157, v156, v157
	v_cvt_pk_bf16_f32 v170, v190, v191
	s_add_i32 s72, s72, 1
	s_add_i32 s79, s79, 0x8000
	s_add_i32 s100, s100, 64
	v_lshl_add_u64 v[218:219], v[218:219], 0, s[88:89]
	v_lshl_add_u64 v[220:221], v[220:221], 0, s[88:89]
	v_lshl_add_u64 v[224:225], v[224:225], 0, s[92:93]
	s_and_b32 s1, s79, 0x18000
	s_xor_b32 s0, s1, 0x10000
	v_add_u32_e32 v158, s0, v222
	v_add_u32_e32 v159, s0, v223
	v_add_u32_e32 v160, s0, v241
	v_add_u32_e32 v161, s0, v242
	s_cmp_ge_i32 s72, s99
	s_cbranch_scc1 .Lk_exit
	s_cmp_ge_i32 s72, s73
	s_cbranch_scc1 .Lk_last
	s_waitcnt vmcnt(4) lgkmcnt(0)
	s_barrier
	s_branch .Lk_top

.Lk_exit:
	s_waitcnt lgkmcnt(4)
	v_mfma_f32_32x32x16_bf16 v[48:63], v[182:185], v[166:169], v[48:63]
	v_add_f32_e32 v202, v255, v92
	v_exp_f32_e32 v202, v202
	v_cvt_pk_bf16_f32 v171, v192, v193
	v_add_f32_e32 v156, v202, v108
	v_add_f32_e32 v157, v156, v157
	v_mfma_f32_32x32x16_bf16 v[32:47], v[178:181], v[166:169], v[32:47]
	v_add_f32_e32 v203, v255, v93
	v_exp_f32_e32 v203, v203
	v_cvt_pk_bf16_f32 v172, v194, v195
	v_add_f32_e32 v156, v203, v109
	v_add_f32_e32 v157, v156, v157
	s_waitcnt lgkmcnt(0)
	v_mfma_f32_32x32x16_bf16 v[16:31], v[148:151], v[166:169], v[16:31]
	v_add_f32_e32 v204, v255, v94
	v_exp_f32_e32 v204, v204
	v_cvt_pk_bf16_f32 v173, v196, v197
	v_add_f32_e32 v156, v204, v110
	v_add_f32_e32 v157, v156, v157
	v_mfma_f32_32x32x16_bf16 v[0:15], v[152:155], v[166:169], v[0:15]
	v_add_f32_e32 v205, v255, v95
	v_exp_f32_e32 v205, v205
	v_cvt_pk_bf16_f32 v166, v198, v199
	v_add_f32_e32 v156, v205, v111
	v_add_f32_e32 v157, v156, v157
	v_cvt_pk_bf16_f32 v167, v200, v201
	v_cvt_pk_bf16_f32 v168, v202, v203
	v_cvt_pk_bf16_f32 v169, v204, v205
	v_add_f32_e32 v229, v229, v157
